# GEMM K-loops: per-segment s_setprio flips removed (both wave groups at priority 0 throughout)
# speedup vs baseline: 1.0022x; 1.0022x over previous
.LBB0_50:
	s_add_u32 s8, s58, 0xfffc0080
	s_addc_u32 s9, s59, -1
	s_add_i32 s10, 0, 0x10000
	s_cmp_eq_u32 s85, 12
	s_cselect_b32 s41, s53, s9
	s_cselect_b32 s40, s69, s8
	s_cselect_b32 s29, s51, s84
	s_cselect_b32 s28, s72, s73
	s_add_i32 s11, 0, 0x14000
	v_add_u32_e32 v158, s10, v150
	v_add_u32_e32 v174, s11, v150
	ds_read_b128 v[142:145], v158
	ds_read_b128 v[146:149], v158 offset:1024
	ds_read_b128 v[154:157], v158 offset:2048
	ds_read_b128 v[158:161], v158 offset:3072
	ds_read_b128 v[162:165], v174
	ds_read_b128 v[166:169], v174 offset:1024
	ds_read_b128 v[170:173], v174 offset:2048
	ds_read_b128 v[174:177], v174 offset:3072
	v_lshl_add_u64 v[210:211], s[58:59], 0, v[138:139]
	s_add_i32 m0, s61, 0xc000
	ds_read_b128 v[178:181], v153
	ds_read_b128 v[182:185], v153 offset:1024
	ds_read_b128 v[186:189], v153 offset:2048
	ds_read_b128 v[190:193], v153 offset:3072
	ds_read_b128 v[194:197], v153 offset:4096
	ds_read_b128 v[198:201], v153 offset:5120
	ds_read_b128 v[202:205], v153 offset:6144
	ds_read_b128 v[206:209], v153 offset:7168
	global_load_lds_dwordx4 v[210:211], off
	v_lshl_add_u64 v[210:211], s[58:59], 0, v[140:141]
	s_add_i32 m0, s61, 0xe000
	s_nop 0
	global_load_lds_dwordx4 v[210:211], off
	s_waitcnt vmcnt(8)
	s_waitcnt lgkmcnt(0)
	s_nop 0
	s_barrier
	v_mfma_f32_16x16x32_bf16 v[126:129], v[142:145], v[178:181], v[126:129]
	v_mfma_f32_16x16x32_bf16 v[118:121], v[154:157], v[178:181], v[118:121]
	v_mfma_f32_16x16x32_bf16 v[110:113], v[142:145], v[186:189], v[110:113]
	v_mfma_f32_16x16x32_bf16 v[102:105], v[154:157], v[186:189], v[102:105]
	v_mfma_f32_16x16x32_bf16 v[94:97], v[142:145], v[194:197], v[94:97]
	v_mfma_f32_16x16x32_bf16 v[86:89], v[154:157], v[194:197], v[86:89]
	v_mfma_f32_16x16x32_bf16 v[78:81], v[142:145], v[202:205], v[78:81]
	v_mfma_f32_16x16x32_bf16 v[70:73], v[154:157], v[202:205], v[70:73]
	v_mfma_f32_16x16x32_bf16 v[126:129], v[146:149], v[182:185], v[126:129]
	v_mfma_f32_16x16x32_bf16 v[118:121], v[158:161], v[182:185], v[118:121]
	v_mfma_f32_16x16x32_bf16 v[110:113], v[146:149], v[190:193], v[110:113]
	v_mfma_f32_16x16x32_bf16 v[102:105], v[158:161], v[190:193], v[102:105]
	v_mfma_f32_16x16x32_bf16 v[94:97], v[146:149], v[198:201], v[94:97]
	v_mfma_f32_16x16x32_bf16 v[86:89], v[158:161], v[198:201], v[86:89]
	v_mfma_f32_16x16x32_bf16 v[78:81], v[146:149], v[206:209], v[78:81]
	v_mfma_f32_16x16x32_bf16 v[70:73], v[158:161], v[206:209], v[70:73]
	v_mfma_f32_16x16x32_bf16 v[122:125], v[162:165], v[178:181], v[122:125]
	v_mfma_f32_16x16x32_bf16 v[114:117], v[170:173], v[178:181], v[114:117]
	v_mfma_f32_16x16x32_bf16 v[106:109], v[162:165], v[186:189], v[106:109]
	v_mfma_f32_16x16x32_bf16 v[98:101], v[170:173], v[186:189], v[98:101]
	v_mfma_f32_16x16x32_bf16 v[90:93], v[162:165], v[194:197], v[90:93]
	v_mfma_f32_16x16x32_bf16 v[82:85], v[170:173], v[194:197], v[82:85]
	v_mfma_f32_16x16x32_bf16 v[74:77], v[162:165], v[202:205], v[74:77]
	v_mfma_f32_16x16x32_bf16 v[66:69], v[170:173], v[202:205], v[66:69]
	v_mfma_f32_16x16x32_bf16 v[122:125], v[166:169], v[182:185], v[122:125]
	v_mfma_f32_16x16x32_bf16 v[114:117], v[174:177], v[182:185], v[114:117]
	v_mfma_f32_16x16x32_bf16 v[106:109], v[166:169], v[190:193], v[106:109]
	v_mfma_f32_16x16x32_bf16 v[98:101], v[174:177], v[190:193], v[98:101]
	v_mfma_f32_16x16x32_bf16 v[90:93], v[166:169], v[198:201], v[90:93]
	v_mfma_f32_16x16x32_bf16 v[82:85], v[174:177], v[198:201], v[82:85]
	v_mfma_f32_16x16x32_bf16 v[74:77], v[166:169], v[206:209], v[74:77]
	v_mfma_f32_16x16x32_bf16 v[66:69], v[174:177], v[206:209], v[66:69]
	s_barrier
	s_nop 0
	s_add_i32 s8, s10, s31
	v_lshl_add_u64 v[210:211], s[28:29], 0, v[130:131]
	s_mov_b32 m0, s8
	ds_read_b128 v[178:181], v153 offset:16384
	ds_read_b128 v[182:185], v153 offset:17408
	ds_read_b128 v[186:189], v153 offset:18432
	ds_read_b128 v[190:193], v153 offset:19456
	ds_read_b128 v[194:197], v153 offset:20480
	ds_read_b128 v[198:201], v153 offset:21504
	ds_read_b128 v[202:205], v153 offset:22528
	ds_read_b128 v[206:209], v153 offset:23552
	global_load_lds_dwordx4 v[210:211], off
	s_add_i32 m0, s8, 0x2000
	s_add_u32 s8, s28, 0x40000
	v_lshl_add_u64 v[212:213], s[28:29], 0, v[132:133]
	s_addc_u32 s9, s29, 0
	s_add_i32 s10, s11, s31
	global_load_lds_dwordx4 v[212:213], off
	v_lshl_add_u64 v[214:215], s[8:9], 0, v[130:131]
	s_mov_b32 m0, s10
	v_lshl_add_u64 v[216:217], s[40:41], 0, v[134:135]
	global_load_lds_dwordx4 v[214:215], off
	v_lshl_add_u64 v[214:215], s[8:9], 0, v[132:133]
	s_add_i32 m0, s10, 0x2000
	s_nop 0
	global_load_lds_dwordx4 v[214:215], off
	v_lshl_add_u64 v[214:215], s[40:41], 0, v[136:137]
	s_mov_b32 m0, s61
	s_nop 0
	global_load_lds_dwordx4 v[214:215], off
	s_mov_b32 m0, s62
	s_nop 0
	global_load_lds_dwordx4 v[216:217], off
	s_waitcnt vmcnt(8)
	s_waitcnt lgkmcnt(0)
	s_nop 0
	s_barrier
	v_mfma_f32_16x16x32_bf16 v[62:65], v[142:145], v[178:181], v[62:65]
	v_mfma_f32_16x16x32_bf16 v[54:57], v[154:157], v[178:181], v[54:57]
	v_mfma_f32_16x16x32_bf16 v[46:49], v[142:145], v[186:189], v[46:49]
	v_mfma_f32_16x16x32_bf16 v[38:41], v[154:157], v[186:189], v[38:41]
	v_mfma_f32_16x16x32_bf16 v[30:33], v[142:145], v[194:197], v[30:33]
	v_mfma_f32_16x16x32_bf16 v[22:25], v[154:157], v[194:197], v[22:25]
	v_mfma_f32_16x16x32_bf16 v[14:17], v[142:145], v[202:205], v[14:17]
	v_mfma_f32_16x16x32_bf16 v[6:9], v[154:157], v[202:205], v[6:9]
	v_mfma_f32_16x16x32_bf16 v[62:65], v[146:149], v[182:185], v[62:65]
	v_mfma_f32_16x16x32_bf16 v[54:57], v[158:161], v[182:185], v[54:57]
	v_mfma_f32_16x16x32_bf16 v[46:49], v[146:149], v[190:193], v[46:49]
	v_mfma_f32_16x16x32_bf16 v[38:41], v[158:161], v[190:193], v[38:41]
	v_mfma_f32_16x16x32_bf16 v[30:33], v[146:149], v[198:201], v[30:33]
	v_mfma_f32_16x16x32_bf16 v[22:25], v[158:161], v[198:201], v[22:25]
	v_mfma_f32_16x16x32_bf16 v[14:17], v[146:149], v[206:209], v[14:17]
	v_mfma_f32_16x16x32_bf16 v[6:9], v[158:161], v[206:209], v[6:9]
	v_mfma_f32_16x16x32_bf16 v[58:61], v[162:165], v[178:181], v[58:61]
	v_mfma_f32_16x16x32_bf16 v[50:53], v[170:173], v[178:181], v[50:53]
	v_mfma_f32_16x16x32_bf16 v[42:45], v[162:165], v[186:189], v[42:45]
	v_mfma_f32_16x16x32_bf16 v[34:37], v[170:173], v[186:189], v[34:37]
	v_mfma_f32_16x16x32_bf16 v[26:29], v[162:165], v[194:197], v[26:29]
	v_mfma_f32_16x16x32_bf16 v[18:21], v[170:173], v[194:197], v[18:21]
	v_mfma_f32_16x16x32_bf16 v[10:13], v[162:165], v[202:205], v[10:13]
	v_mfma_f32_16x16x32_bf16 v[2:5], v[170:173], v[202:205], v[2:5]
	v_mfma_f32_16x16x32_bf16 v[58:61], v[166:169], v[182:185], v[58:61]
	v_mfma_f32_16x16x32_bf16 v[50:53], v[174:177], v[182:185], v[50:53]
	v_mfma_f32_16x16x32_bf16 v[42:45], v[166:169], v[190:193], v[42:45]
	v_mfma_f32_16x16x32_bf16 v[34:37], v[174:177], v[190:193], v[34:37]
	v_mfma_f32_16x16x32_bf16 v[26:29], v[166:169], v[198:201], v[26:29]
	v_mfma_f32_16x16x32_bf16 v[18:21], v[174:177], v[198:201], v[18:21]
	v_mfma_f32_16x16x32_bf16 v[10:13], v[166:169], v[206:209], v[10:13]
	v_mfma_f32_16x16x32_bf16 v[2:5], v[174:177], v[206:209], v[2:5]
	s_barrier
	s_nop 0
	s_add_i32 s10, 0, 0x18000
	s_add_i32 s11, 0, 0x1c000
	v_add_u32_e32 v158, s10, v150
	v_add_u32_e32 v174, s11, v150
	ds_read_b128 v[142:145], v158
	ds_read_b128 v[146:149], v158 offset:1024
	ds_read_b128 v[154:157], v158 offset:2048
	ds_read_b128 v[158:161], v158 offset:3072
	ds_read_b128 v[162:165], v174
	ds_read_b128 v[166:169], v174 offset:1024
	ds_read_b128 v[170:173], v174 offset:2048
	ds_read_b128 v[174:177], v174 offset:3072
	s_add_u32 s8, s40, 0x40000
	s_addc_u32 s9, s41, 0
	s_mov_b32 m0, s63
	v_lshl_add_u64 v[218:219], s[8:9], 0, v[136:137]
	ds_read_b128 v[178:181], v153 offset:32768
	ds_read_b128 v[182:185], v153 offset:33792
	ds_read_b128 v[186:189], v153 offset:34816
	ds_read_b128 v[190:193], v153 offset:35840
	ds_read_b128 v[194:197], v153 offset:36864
	ds_read_b128 v[198:201], v153 offset:37888
	ds_read_b128 v[202:205], v153 offset:38912
	ds_read_b128 v[206:209], v153 offset:39936
	global_load_lds_dwordx4 v[218:219], off
	v_lshl_add_u64 v[218:219], s[8:9], 0, v[134:135]
	s_mov_b32 m0, s64
	s_nop 0
	global_load_lds_dwordx4 v[218:219], off
	s_waitcnt vmcnt(8)
	s_waitcnt lgkmcnt(0)
	s_nop 0
	s_barrier
	v_mfma_f32_16x16x32_bf16 v[126:129], v[142:145], v[178:181], v[126:129]
	v_mfma_f32_16x16x32_bf16 v[118:121], v[154:157], v[178:181], v[118:121]
	v_mfma_f32_16x16x32_bf16 v[110:113], v[142:145], v[186:189], v[110:113]
	v_mfma_f32_16x16x32_bf16 v[102:105], v[154:157], v[186:189], v[102:105]
	v_mfma_f32_16x16x32_bf16 v[94:97], v[142:145], v[194:197], v[94:97]
	v_mfma_f32_16x16x32_bf16 v[86:89], v[154:157], v[194:197], v[86:89]
	v_mfma_f32_16x16x32_bf16 v[78:81], v[142:145], v[202:205], v[78:81]
	v_mfma_f32_16x16x32_bf16 v[70:73], v[154:157], v[202:205], v[70:73]
	v_mfma_f32_16x16x32_bf16 v[126:129], v[146:149], v[182:185], v[126:129]
	v_mfma_f32_16x16x32_bf16 v[118:121], v[158:161], v[182:185], v[118:121]
	v_mfma_f32_16x16x32_bf16 v[110:113], v[146:149], v[190:193], v[110:113]
	v_mfma_f32_16x16x32_bf16 v[102:105], v[158:161], v[190:193], v[102:105]
	v_mfma_f32_16x16x32_bf16 v[94:97], v[146:149], v[198:201], v[94:97]
	v_mfma_f32_16x16x32_bf16 v[86:89], v[158:161], v[198:201], v[86:89]
	v_mfma_f32_16x16x32_bf16 v[78:81], v[146:149], v[206:209], v[78:81]
	v_mfma_f32_16x16x32_bf16 v[70:73], v[158:161], v[206:209], v[70:73]
	v_mfma_f32_16x16x32_bf16 v[122:125], v[162:165], v[178:181], v[122:125]
	v_mfma_f32_16x16x32_bf16 v[114:117], v[170:173], v[178:181], v[114:117]
	v_mfma_f32_16x16x32_bf16 v[106:109], v[162:165], v[186:189], v[106:109]
	v_mfma_f32_16x16x32_bf16 v[98:101], v[170:173], v[186:189], v[98:101]
	v_mfma_f32_16x16x32_bf16 v[90:93], v[162:165], v[194:197], v[90:93]
	v_mfma_f32_16x16x32_bf16 v[82:85], v[170:173], v[194:197], v[82:85]
	v_mfma_f32_16x16x32_bf16 v[74:77], v[162:165], v[202:205], v[74:77]
	v_mfma_f32_16x16x32_bf16 v[66:69], v[170:173], v[202:205], v[66:69]
	v_mfma_f32_16x16x32_bf16 v[122:125], v[166:169], v[182:185], v[122:125]
	v_mfma_f32_16x16x32_bf16 v[114:117], v[174:177], v[182:185], v[114:117]
	v_mfma_f32_16x16x32_bf16 v[106:109], v[166:169], v[190:193], v[106:109]
	v_mfma_f32_16x16x32_bf16 v[98:101], v[174:177], v[190:193], v[98:101]
	v_mfma_f32_16x16x32_bf16 v[90:93], v[166:169], v[198:201], v[90:93]
	v_mfma_f32_16x16x32_bf16 v[82:85], v[174:177], v[198:201], v[82:85]
	v_mfma_f32_16x16x32_bf16 v[74:77], v[166:169], v[206:209], v[74:77]
	v_mfma_f32_16x16x32_bf16 v[66:69], v[174:177], v[206:209], v[66:69]
	s_barrier
	s_nop 0
	s_add_i32 s8, s10, s31
	v_lshl_add_u64 v[210:211], v[210:211], 0, s[82:83]
	s_mov_b32 m0, s8
	ds_read_b128 v[178:181], v153 offset:49152
	ds_read_b128 v[182:185], v153 offset:50176
	ds_read_b128 v[186:189], v153 offset:51200
	ds_read_b128 v[190:193], v153 offset:52224
	ds_read_b128 v[194:197], v153 offset:53248
	ds_read_b128 v[198:201], v153 offset:54272
	ds_read_b128 v[202:205], v153 offset:55296
	ds_read_b128 v[206:209], v153 offset:56320
	global_load_lds_dwordx4 v[210:211], off
	s_add_i32 m0, s8, 0x2000
	s_add_u32 s8, s28, 0x40080
	v_lshl_add_u64 v[210:211], v[212:213], 0, s[82:83]
	s_addc_u32 s9, s29, 0
	s_add_i32 s10, s11, s31
	global_load_lds_dwordx4 v[210:211], off
	v_lshl_add_u64 v[210:211], s[8:9], 0, v[130:131]
	s_mov_b32 m0, s10
	s_nop 0
	global_load_lds_dwordx4 v[210:211], off
	v_lshl_add_u64 v[210:211], s[8:9], 0, v[132:133]
	s_add_i32 m0, s10, 0x2000
	s_nop 0
	global_load_lds_dwordx4 v[210:211], off
	v_lshl_add_u64 v[210:211], v[214:215], 0, s[82:83]
	s_mov_b32 m0, s65
	s_nop 0
	global_load_lds_dwordx4 v[210:211], off
	v_lshl_add_u64 v[210:211], v[216:217], 0, s[82:83]
	s_mov_b32 m0, s66
	s_nop 0
	global_load_lds_dwordx4 v[210:211], off
	s_waitcnt vmcnt(8)
	s_waitcnt lgkmcnt(0)
	s_nop 0
	s_barrier
	v_mfma_f32_16x16x32_bf16 v[62:65], v[142:145], v[178:181], v[62:65]
	v_mfma_f32_16x16x32_bf16 v[54:57], v[154:157], v[178:181], v[54:57]
	v_mfma_f32_16x16x32_bf16 v[46:49], v[142:145], v[186:189], v[46:49]
	v_mfma_f32_16x16x32_bf16 v[38:41], v[154:157], v[186:189], v[38:41]
	v_mfma_f32_16x16x32_bf16 v[30:33], v[142:145], v[194:197], v[30:33]
	v_mfma_f32_16x16x32_bf16 v[22:25], v[154:157], v[194:197], v[22:25]
	v_mfma_f32_16x16x32_bf16 v[14:17], v[142:145], v[202:205], v[14:17]
	v_mfma_f32_16x16x32_bf16 v[6:9], v[154:157], v[202:205], v[6:9]
	v_mfma_f32_16x16x32_bf16 v[62:65], v[146:149], v[182:185], v[62:65]
	v_mfma_f32_16x16x32_bf16 v[54:57], v[158:161], v[182:185], v[54:57]
	v_mfma_f32_16x16x32_bf16 v[46:49], v[146:149], v[190:193], v[46:49]
	v_mfma_f32_16x16x32_bf16 v[38:41], v[158:161], v[190:193], v[38:41]
	v_mfma_f32_16x16x32_bf16 v[30:33], v[146:149], v[198:201], v[30:33]
	v_mfma_f32_16x16x32_bf16 v[22:25], v[158:161], v[198:201], v[22:25]
	v_mfma_f32_16x16x32_bf16 v[14:17], v[146:149], v[206:209], v[14:17]
	v_mfma_f32_16x16x32_bf16 v[6:9], v[158:161], v[206:209], v[6:9]
	v_mfma_f32_16x16x32_bf16 v[58:61], v[162:165], v[178:181], v[58:61]
	v_mfma_f32_16x16x32_bf16 v[50:53], v[170:173], v[178:181], v[50:53]
	v_mfma_f32_16x16x32_bf16 v[42:45], v[162:165], v[186:189], v[42:45]
	v_mfma_f32_16x16x32_bf16 v[34:37], v[170:173], v[186:189], v[34:37]
	v_mfma_f32_16x16x32_bf16 v[26:29], v[162:165], v[194:197], v[26:29]
	v_mfma_f32_16x16x32_bf16 v[18:21], v[170:173], v[194:197], v[18:21]
	v_mfma_f32_16x16x32_bf16 v[10:13], v[162:165], v[202:205], v[10:13]
	v_mfma_f32_16x16x32_bf16 v[2:5], v[170:173], v[202:205], v[2:5]
	v_mfma_f32_16x16x32_bf16 v[58:61], v[166:169], v[182:185], v[58:61]
	v_mfma_f32_16x16x32_bf16 v[50:53], v[174:177], v[182:185], v[50:53]
	v_mfma_f32_16x16x32_bf16 v[42:45], v[166:169], v[190:193], v[42:45]
	v_mfma_f32_16x16x32_bf16 v[34:37], v[174:177], v[190:193], v[34:37]
	v_mfma_f32_16x16x32_bf16 v[26:29], v[166:169], v[198:201], v[26:29]
	v_mfma_f32_16x16x32_bf16 v[18:21], v[174:177], v[198:201], v[18:21]
	v_mfma_f32_16x16x32_bf16 v[10:13], v[166:169], v[206:209], v[10:13]
	v_mfma_f32_16x16x32_bf16 v[2:5], v[174:177], v[206:209], v[2:5]
	s_barrier
	s_nop 0
	s_add_i32 s85, s85, 2
	s_add_u32 s58, s58, 0x100
	s_addc_u32 s59, s59, 0
	s_add_u32 s73, s73, 0x100
	s_addc_u32 s84, s84, 0
	s_cmp_gt_u32 s85, 13
	s_cbranch_scc0 .LBB0_50
	s_and_b64 vcc, exec, s[48:49]
	s_cbranch_vccz .LBB0_53
	s_barrier

.LBB0_75:
	s_add_i32 s41, s28, 2
	s_add_u32 s8, s60, 0x80
	s_addc_u32 s9, s61, 0
	s_add_i32 s10, 0, 0x10000
	s_cmp_eq_u32 s84, s28
	s_cselect_b32 s29, s47, s9
	s_cselect_b32 s28, s46, s8
	s_cselect_b32 s9, s59, s40
	s_cselect_b32 s8, s58, s7
	s_add_i32 s11, 0, 0x14000
	v_add_u32_e32 v126, s10, v1
	v_add_u32_e32 v160, s11, v1
	ds_read_b128 v[98:101], v126
	ds_read_b128 v[102:105], v126 offset:1024
	ds_read_b128 v[122:125], v126 offset:2048
	ds_read_b128 v[126:129], v126 offset:3072
	ds_read_b128 v[144:147], v160
	ds_read_b128 v[148:151], v160 offset:1024
	ds_read_b128 v[156:159], v160 offset:2048
	ds_read_b128 v[160:163], v160 offset:3072
	v_lshl_add_u64 v[206:207], s[60:61], 0, v[194:195]
	s_add_i32 m0, s66, 0xc000
	ds_read_b128 v[164:167], v231
	ds_read_b128 v[168:171], v231 offset:1024
	ds_read_b128 v[172:175], v231 offset:2048
	ds_read_b128 v[176:179], v231 offset:3072
	ds_read_b128 v[180:183], v231 offset:4096
	ds_read_b128 v[184:187], v231 offset:5120
	ds_read_b128 v[198:201], v231 offset:6144
	ds_read_b128 v[202:205], v231 offset:7168
	global_load_lds_dwordx4 v[206:207], off
	v_lshl_add_u64 v[206:207], s[60:61], 0, v[196:197]
	s_add_i32 m0, s66, 0xe000
	s_nop 0
	global_load_lds_dwordx4 v[206:207], off
	s_waitcnt vmcnt(8)
	s_waitcnt lgkmcnt(0)
	s_nop 0
	s_barrier
	v_mfma_f32_16x16x32_bf16 v[152:155], v[98:101], v[164:167], v[152:155]
	v_mfma_f32_16x16x32_bf16 v[140:143], v[122:125], v[164:167], v[140:143]
	v_mfma_f32_16x16x32_bf16 v[118:121], v[98:101], v[172:175], v[118:121]
	v_mfma_f32_16x16x32_bf16 v[114:117], v[122:125], v[172:175], v[114:117]
	v_mfma_f32_16x16x32_bf16 v[94:97], v[98:101], v[180:183], v[94:97]
	v_mfma_f32_16x16x32_bf16 v[90:93], v[122:125], v[180:183], v[90:93]
	v_mfma_f32_16x16x32_bf16 v[78:81], v[98:101], v[198:201], v[78:81]
	v_mfma_f32_16x16x32_bf16 v[74:77], v[122:125], v[198:201], v[74:77]
	v_mfma_f32_16x16x32_bf16 v[152:155], v[102:105], v[168:171], v[152:155]
	v_mfma_f32_16x16x32_bf16 v[140:143], v[126:129], v[168:171], v[140:143]
	v_mfma_f32_16x16x32_bf16 v[118:121], v[102:105], v[176:179], v[118:121]
	v_mfma_f32_16x16x32_bf16 v[114:117], v[126:129], v[176:179], v[114:117]
	v_mfma_f32_16x16x32_bf16 v[94:97], v[102:105], v[184:187], v[94:97]
	v_mfma_f32_16x16x32_bf16 v[90:93], v[126:129], v[184:187], v[90:93]
	v_mfma_f32_16x16x32_bf16 v[78:81], v[102:105], v[202:205], v[78:81]
	v_mfma_f32_16x16x32_bf16 v[74:77], v[126:129], v[202:205], v[74:77]
	v_mfma_f32_16x16x32_bf16 v[136:139], v[144:147], v[164:167], v[136:139]
	v_mfma_f32_16x16x32_bf16 v[132:135], v[156:159], v[164:167], v[132:135]
	v_mfma_f32_16x16x32_bf16 v[110:113], v[144:147], v[172:175], v[110:113]
	v_mfma_f32_16x16x32_bf16 v[106:109], v[156:159], v[172:175], v[106:109]
	v_mfma_f32_16x16x32_bf16 v[86:89], v[144:147], v[180:183], v[86:89]
	v_mfma_f32_16x16x32_bf16 v[82:85], v[156:159], v[180:183], v[82:85]
	v_mfma_f32_16x16x32_bf16 v[70:73], v[144:147], v[198:201], v[70:73]
	v_mfma_f32_16x16x32_bf16 v[66:69], v[156:159], v[198:201], v[66:69]
	v_mfma_f32_16x16x32_bf16 v[136:139], v[148:151], v[168:171], v[136:139]
	v_mfma_f32_16x16x32_bf16 v[132:135], v[160:163], v[168:171], v[132:135]
	v_mfma_f32_16x16x32_bf16 v[110:113], v[148:151], v[176:179], v[110:113]
	v_mfma_f32_16x16x32_bf16 v[106:109], v[160:163], v[176:179], v[106:109]
	v_mfma_f32_16x16x32_bf16 v[86:89], v[148:151], v[184:187], v[86:89]
	v_mfma_f32_16x16x32_bf16 v[82:85], v[160:163], v[184:187], v[82:85]
	v_mfma_f32_16x16x32_bf16 v[70:73], v[148:151], v[202:205], v[70:73]
	v_mfma_f32_16x16x32_bf16 v[66:69], v[160:163], v[202:205], v[66:69]
	s_barrier
	s_nop 0
	s_add_i32 s10, s10, s64
	v_lshl_add_u64 v[206:207], s[8:9], 0, v[130:131]
	s_mov_b32 m0, s10
	ds_read_b128 v[164:167], v231 offset:16384
	ds_read_b128 v[168:171], v231 offset:17408
	ds_read_b128 v[172:175], v231 offset:18432
	ds_read_b128 v[176:179], v231 offset:19456
	ds_read_b128 v[180:183], v231 offset:20480
	ds_read_b128 v[184:187], v231 offset:21504
	ds_read_b128 v[198:201], v231 offset:22528
	ds_read_b128 v[202:205], v231 offset:23552
	global_load_lds_dwordx4 v[206:207], off
	s_add_i32 m0, s10, 0x2000
	v_lshl_add_u64 v[208:209], s[8:9], 0, v[188:189]
	s_add_u32 s8, s8, s48
	s_addc_u32 s9, s9, 0
	s_add_i32 s10, s11, s64
	global_load_lds_dwordx4 v[208:209], off
	v_lshl_add_u64 v[210:211], s[8:9], 0, v[130:131]
	s_mov_b32 m0, s10
	v_lshl_add_u64 v[212:213], s[8:9], 0, v[188:189]
	global_load_lds_dwordx4 v[210:211], off
	s_add_i32 m0, s10, 0x2000
	v_lshl_add_u64 v[214:215], s[28:29], 0, v[192:193]
	global_load_lds_dwordx4 v[212:213], off
	s_mov_b32 m0, s66
	v_lshl_add_u64 v[216:217], s[28:29], 0, v[190:191]
	global_load_lds_dwordx4 v[214:215], off
	s_mov_b32 m0, s67
	s_nop 0
	global_load_lds_dwordx4 v[216:217], off
	s_waitcnt vmcnt(8)
	s_waitcnt lgkmcnt(0)
	s_nop 0
	s_barrier
	v_mfma_f32_16x16x32_bf16 v[62:65], v[98:101], v[164:167], v[62:65]
	v_mfma_f32_16x16x32_bf16 v[58:61], v[122:125], v[164:167], v[58:61]
	v_mfma_f32_16x16x32_bf16 v[46:49], v[98:101], v[172:175], v[46:49]
	v_mfma_f32_16x16x32_bf16 v[42:45], v[122:125], v[172:175], v[42:45]
	v_mfma_f32_16x16x32_bf16 v[30:33], v[98:101], v[180:183], v[30:33]
	v_mfma_f32_16x16x32_bf16 v[26:29], v[122:125], v[180:183], v[26:29]
	v_mfma_f32_16x16x32_bf16 v[14:17], v[98:101], v[198:201], v[14:17]
	v_mfma_f32_16x16x32_bf16 v[10:13], v[122:125], v[198:201], v[10:13]
	v_mfma_f32_16x16x32_bf16 v[62:65], v[102:105], v[168:171], v[62:65]
	v_mfma_f32_16x16x32_bf16 v[58:61], v[126:129], v[168:171], v[58:61]
	v_mfma_f32_16x16x32_bf16 v[46:49], v[102:105], v[176:179], v[46:49]
	v_mfma_f32_16x16x32_bf16 v[42:45], v[126:129], v[176:179], v[42:45]
	v_mfma_f32_16x16x32_bf16 v[30:33], v[102:105], v[184:187], v[30:33]
	v_mfma_f32_16x16x32_bf16 v[26:29], v[126:129], v[184:187], v[26:29]
	v_mfma_f32_16x16x32_bf16 v[14:17], v[102:105], v[202:205], v[14:17]
	v_mfma_f32_16x16x32_bf16 v[10:13], v[126:129], v[202:205], v[10:13]
	v_mfma_f32_16x16x32_bf16 v[54:57], v[144:147], v[164:167], v[54:57]
	v_mfma_f32_16x16x32_bf16 v[50:53], v[156:159], v[164:167], v[50:53]
	v_mfma_f32_16x16x32_bf16 v[38:41], v[144:147], v[172:175], v[38:41]
	v_mfma_f32_16x16x32_bf16 v[34:37], v[156:159], v[172:175], v[34:37]
	v_mfma_f32_16x16x32_bf16 v[22:25], v[144:147], v[180:183], v[22:25]
	v_mfma_f32_16x16x32_bf16 v[18:21], v[156:159], v[180:183], v[18:21]
	v_mfma_f32_16x16x32_bf16 v[6:9], v[144:147], v[198:201], v[6:9]
	v_mfma_f32_16x16x32_bf16 v[2:5], v[156:159], v[198:201], v[2:5]
	v_mfma_f32_16x16x32_bf16 v[54:57], v[148:151], v[168:171], v[54:57]
	v_mfma_f32_16x16x32_bf16 v[50:53], v[160:163], v[168:171], v[50:53]
	v_mfma_f32_16x16x32_bf16 v[38:41], v[148:151], v[176:179], v[38:41]
	v_mfma_f32_16x16x32_bf16 v[34:37], v[160:163], v[176:179], v[34:37]
	v_mfma_f32_16x16x32_bf16 v[22:25], v[148:151], v[184:187], v[22:25]
	v_mfma_f32_16x16x32_bf16 v[18:21], v[160:163], v[184:187], v[18:21]
	v_mfma_f32_16x16x32_bf16 v[6:9], v[148:151], v[202:205], v[6:9]
	v_mfma_f32_16x16x32_bf16 v[2:5], v[160:163], v[202:205], v[2:5]
	s_barrier
	s_nop 0
	s_add_i32 s10, 0, 0x18000
	s_add_i32 s11, 0, 0x1c000
	v_add_u32_e32 v126, s10, v1
	v_add_u32_e32 v160, s11, v1
	ds_read_b128 v[98:101], v126
	ds_read_b128 v[102:105], v126 offset:1024
	ds_read_b128 v[122:125], v126 offset:2048
	ds_read_b128 v[126:129], v126 offset:3072
	ds_read_b128 v[144:147], v160
	ds_read_b128 v[148:151], v160 offset:1024
	ds_read_b128 v[156:159], v160 offset:2048
	ds_read_b128 v[160:163], v160 offset:3072
	s_add_u32 s8, s28, s48
	s_addc_u32 s9, s29, 0
	s_mov_b32 m0, s68
	v_lshl_add_u64 v[218:219], s[8:9], 0, v[192:193]
	ds_read_b128 v[164:167], v231 offset:32768
	ds_read_b128 v[168:171], v231 offset:33792
	ds_read_b128 v[172:175], v231 offset:34816
	ds_read_b128 v[176:179], v231 offset:35840
	ds_read_b128 v[180:183], v231 offset:36864
	ds_read_b128 v[184:187], v231 offset:37888
	ds_read_b128 v[198:201], v231 offset:38912
	ds_read_b128 v[202:205], v231 offset:39936
	global_load_lds_dwordx4 v[218:219], off
	v_lshl_add_u64 v[218:219], s[8:9], 0, v[190:191]
	s_mov_b32 m0, s69
	s_nop 0
	global_load_lds_dwordx4 v[218:219], off
	s_waitcnt vmcnt(8)
	s_waitcnt lgkmcnt(0)
	s_nop 0
	s_barrier
	v_mfma_f32_16x16x32_bf16 v[152:155], v[98:101], v[164:167], v[152:155]
	v_mfma_f32_16x16x32_bf16 v[140:143], v[122:125], v[164:167], v[140:143]
	v_mfma_f32_16x16x32_bf16 v[118:121], v[98:101], v[172:175], v[118:121]
	v_mfma_f32_16x16x32_bf16 v[114:117], v[122:125], v[172:175], v[114:117]
	v_mfma_f32_16x16x32_bf16 v[94:97], v[98:101], v[180:183], v[94:97]
	v_mfma_f32_16x16x32_bf16 v[90:93], v[122:125], v[180:183], v[90:93]
	v_mfma_f32_16x16x32_bf16 v[78:81], v[98:101], v[198:201], v[78:81]
	v_mfma_f32_16x16x32_bf16 v[74:77], v[122:125], v[198:201], v[74:77]
	v_mfma_f32_16x16x32_bf16 v[152:155], v[102:105], v[168:171], v[152:155]
	v_mfma_f32_16x16x32_bf16 v[140:143], v[126:129], v[168:171], v[140:143]
	v_mfma_f32_16x16x32_bf16 v[118:121], v[102:105], v[176:179], v[118:121]
	v_mfma_f32_16x16x32_bf16 v[114:117], v[126:129], v[176:179], v[114:117]
	v_mfma_f32_16x16x32_bf16 v[94:97], v[102:105], v[184:187], v[94:97]
	v_mfma_f32_16x16x32_bf16 v[90:93], v[126:129], v[184:187], v[90:93]
	v_mfma_f32_16x16x32_bf16 v[78:81], v[102:105], v[202:205], v[78:81]
	v_mfma_f32_16x16x32_bf16 v[74:77], v[126:129], v[202:205], v[74:77]
	v_mfma_f32_16x16x32_bf16 v[136:139], v[144:147], v[164:167], v[136:139]
	v_mfma_f32_16x16x32_bf16 v[132:135], v[156:159], v[164:167], v[132:135]
	v_mfma_f32_16x16x32_bf16 v[110:113], v[144:147], v[172:175], v[110:113]
	v_mfma_f32_16x16x32_bf16 v[106:109], v[156:159], v[172:175], v[106:109]
	v_mfma_f32_16x16x32_bf16 v[86:89], v[144:147], v[180:183], v[86:89]
	v_mfma_f32_16x16x32_bf16 v[82:85], v[156:159], v[180:183], v[82:85]
	v_mfma_f32_16x16x32_bf16 v[70:73], v[144:147], v[198:201], v[70:73]
	v_mfma_f32_16x16x32_bf16 v[66:69], v[156:159], v[198:201], v[66:69]
	v_mfma_f32_16x16x32_bf16 v[136:139], v[148:151], v[168:171], v[136:139]
	v_mfma_f32_16x16x32_bf16 v[132:135], v[160:163], v[168:171], v[132:135]
	v_mfma_f32_16x16x32_bf16 v[110:113], v[148:151], v[176:179], v[110:113]
	v_mfma_f32_16x16x32_bf16 v[106:109], v[160:163], v[176:179], v[106:109]
	v_mfma_f32_16x16x32_bf16 v[86:89], v[148:151], v[184:187], v[86:89]
	v_mfma_f32_16x16x32_bf16 v[82:85], v[160:163], v[184:187], v[82:85]
	v_mfma_f32_16x16x32_bf16 v[70:73], v[148:151], v[202:205], v[70:73]
	v_mfma_f32_16x16x32_bf16 v[66:69], v[160:163], v[202:205], v[66:69]
	s_barrier
	s_nop 0
	s_add_i32 s8, s10, s64
	v_lshl_add_u64 v[206:207], v[206:207], 0, s[82:83]
	s_mov_b32 m0, s8
	ds_read_b128 v[164:167], v231 offset:49152
	ds_read_b128 v[168:171], v231 offset:50176
	ds_read_b128 v[172:175], v231 offset:51200
	ds_read_b128 v[176:179], v231 offset:52224
	ds_read_b128 v[180:183], v231 offset:53248
	ds_read_b128 v[184:187], v231 offset:54272
	ds_read_b128 v[198:201], v231 offset:55296
	ds_read_b128 v[202:205], v231 offset:56320
	global_load_lds_dwordx4 v[206:207], off
	v_lshl_add_u64 v[206:207], v[208:209], 0, s[82:83]
	s_add_i32 m0, s8, 0x2000
	s_add_i32 s8, s11, s64
	global_load_lds_dwordx4 v[206:207], off
	v_lshl_add_u64 v[206:207], v[210:211], 0, s[82:83]
	s_mov_b32 m0, s8
	s_nop 0
	global_load_lds_dwordx4 v[206:207], off
	v_lshl_add_u64 v[206:207], v[212:213], 0, s[82:83]
	s_add_i32 m0, s8, 0x2000
	s_nop 0
	global_load_lds_dwordx4 v[206:207], off
	v_lshl_add_u64 v[206:207], v[214:215], 0, s[82:83]
	s_mov_b32 m0, s85
	s_nop 0
	global_load_lds_dwordx4 v[206:207], off
	v_lshl_add_u64 v[206:207], v[216:217], 0, s[82:83]
	s_mov_b32 m0, s88
	s_nop 0
	global_load_lds_dwordx4 v[206:207], off
	s_waitcnt vmcnt(8)
	s_waitcnt lgkmcnt(0)
	s_nop 0
	s_barrier
	v_mfma_f32_16x16x32_bf16 v[62:65], v[98:101], v[164:167], v[62:65]
	v_mfma_f32_16x16x32_bf16 v[58:61], v[122:125], v[164:167], v[58:61]
	v_mfma_f32_16x16x32_bf16 v[46:49], v[98:101], v[172:175], v[46:49]
	v_mfma_f32_16x16x32_bf16 v[42:45], v[122:125], v[172:175], v[42:45]
	v_mfma_f32_16x16x32_bf16 v[30:33], v[98:101], v[180:183], v[30:33]
	v_mfma_f32_16x16x32_bf16 v[26:29], v[122:125], v[180:183], v[26:29]
	v_mfma_f32_16x16x32_bf16 v[14:17], v[98:101], v[198:201], v[14:17]
	v_mfma_f32_16x16x32_bf16 v[10:13], v[122:125], v[198:201], v[10:13]
	v_mfma_f32_16x16x32_bf16 v[62:65], v[102:105], v[168:171], v[62:65]
	v_mfma_f32_16x16x32_bf16 v[58:61], v[126:129], v[168:171], v[58:61]
	v_mfma_f32_16x16x32_bf16 v[46:49], v[102:105], v[176:179], v[46:49]
	v_mfma_f32_16x16x32_bf16 v[42:45], v[126:129], v[176:179], v[42:45]
	v_mfma_f32_16x16x32_bf16 v[30:33], v[102:105], v[184:187], v[30:33]
	v_mfma_f32_16x16x32_bf16 v[26:29], v[126:129], v[184:187], v[26:29]
	v_mfma_f32_16x16x32_bf16 v[14:17], v[102:105], v[202:205], v[14:17]
	v_mfma_f32_16x16x32_bf16 v[10:13], v[126:129], v[202:205], v[10:13]
	v_mfma_f32_16x16x32_bf16 v[54:57], v[144:147], v[164:167], v[54:57]
	v_mfma_f32_16x16x32_bf16 v[50:53], v[156:159], v[164:167], v[50:53]
	v_mfma_f32_16x16x32_bf16 v[38:41], v[144:147], v[172:175], v[38:41]
	v_mfma_f32_16x16x32_bf16 v[34:37], v[156:159], v[172:175], v[34:37]
	v_mfma_f32_16x16x32_bf16 v[22:25], v[144:147], v[180:183], v[22:25]
	v_mfma_f32_16x16x32_bf16 v[18:21], v[156:159], v[180:183], v[18:21]
	v_mfma_f32_16x16x32_bf16 v[6:9], v[144:147], v[198:201], v[6:9]
	v_mfma_f32_16x16x32_bf16 v[2:5], v[156:159], v[198:201], v[2:5]
	v_mfma_f32_16x16x32_bf16 v[54:57], v[148:151], v[168:171], v[54:57]
	v_mfma_f32_16x16x32_bf16 v[50:53], v[160:163], v[168:171], v[50:53]
	v_mfma_f32_16x16x32_bf16 v[38:41], v[148:151], v[176:179], v[38:41]
	v_mfma_f32_16x16x32_bf16 v[34:37], v[160:163], v[176:179], v[34:37]
	v_mfma_f32_16x16x32_bf16 v[22:25], v[148:151], v[184:187], v[22:25]
	v_mfma_f32_16x16x32_bf16 v[18:21], v[160:163], v[184:187], v[18:21]
	v_mfma_f32_16x16x32_bf16 v[6:9], v[148:151], v[202:205], v[6:9]
	v_mfma_f32_16x16x32_bf16 v[2:5], v[160:163], v[202:205], v[2:5]
	s_barrier
	s_nop 0
	s_add_u32 s60, s60, 0x100
	s_addc_u32 s61, s61, 0
	s_add_u32 s7, s7, 0x100
	s_addc_u32 s40, s40, 0
	s_cmp_ge_u32 s41, s73
	s_mov_b32 s28, s41
	s_cbranch_scc0 .LBB0_75
	s_and_b64 vcc, exec, s[54:55]
	s_cbranch_vccz .LBB0_78
	s_barrier

.LBB0_497:
	s_add_u32 s8, s60, 0xfffc0080
	s_addc_u32 s9, s61, -1
	s_add_i32 s10, 0, 0x10000
	s_cmp_eq_u32 s84, 12
	s_cselect_b32 s41, s55, s9
	s_cselect_b32 s40, s72, s8
	s_cselect_b32 s29, s53, s77
	s_cselect_b32 s28, s73, s76
	s_add_i32 s11, 0, 0x14000
	v_add_u32_e32 v158, s10, v1
	v_add_u32_e32 v174, s11, v1
	ds_read_b128 v[146:149], v158
	ds_read_b128 v[150:153], v158 offset:1024
	ds_read_b128 v[154:157], v158 offset:2048
	ds_read_b128 v[158:161], v158 offset:3072
	ds_read_b128 v[162:165], v174
	ds_read_b128 v[166:169], v174 offset:1024
	ds_read_b128 v[170:173], v174 offset:2048
	ds_read_b128 v[174:177], v174 offset:3072
	v_lshl_add_u64 v[210:211], s[60:61], 0, v[138:139]
	s_add_i32 m0, s62, 0xc000
	ds_read_b128 v[178:181], v145
	ds_read_b128 v[182:185], v145 offset:1024
	ds_read_b128 v[186:189], v145 offset:2048
	ds_read_b128 v[190:193], v145 offset:3072
	ds_read_b128 v[194:197], v145 offset:4096
	ds_read_b128 v[198:201], v145 offset:5120
	ds_read_b128 v[202:205], v145 offset:6144
	ds_read_b128 v[206:209], v145 offset:7168
	global_load_lds_dwordx4 v[210:211], off
	v_lshl_add_u64 v[210:211], s[60:61], 0, v[140:141]
	s_add_i32 m0, s62, 0xe000
	s_nop 0
	global_load_lds_dwordx4 v[210:211], off
	s_waitcnt vmcnt(8)
	s_waitcnt lgkmcnt(0)
	s_nop 0
	s_barrier
	v_mfma_f32_16x16x32_bf16 v[126:129], v[146:149], v[178:181], v[126:129]
	v_mfma_f32_16x16x32_bf16 v[122:125], v[154:157], v[178:181], v[122:125]
	v_mfma_f32_16x16x32_bf16 v[110:113], v[146:149], v[186:189], v[110:113]
	v_mfma_f32_16x16x32_bf16 v[106:109], v[154:157], v[186:189], v[106:109]
	v_mfma_f32_16x16x32_bf16 v[94:97], v[146:149], v[194:197], v[94:97]
	v_mfma_f32_16x16x32_bf16 v[90:93], v[154:157], v[194:197], v[90:93]
	v_mfma_f32_16x16x32_bf16 v[78:81], v[146:149], v[202:205], v[78:81]
	v_mfma_f32_16x16x32_bf16 v[74:77], v[154:157], v[202:205], v[74:77]
	v_mfma_f32_16x16x32_bf16 v[126:129], v[150:153], v[182:185], v[126:129]
	v_mfma_f32_16x16x32_bf16 v[122:125], v[158:161], v[182:185], v[122:125]
	v_mfma_f32_16x16x32_bf16 v[110:113], v[150:153], v[190:193], v[110:113]
	v_mfma_f32_16x16x32_bf16 v[106:109], v[158:161], v[190:193], v[106:109]
	v_mfma_f32_16x16x32_bf16 v[94:97], v[150:153], v[198:201], v[94:97]
	v_mfma_f32_16x16x32_bf16 v[90:93], v[158:161], v[198:201], v[90:93]
	v_mfma_f32_16x16x32_bf16 v[78:81], v[150:153], v[206:209], v[78:81]
	v_mfma_f32_16x16x32_bf16 v[74:77], v[158:161], v[206:209], v[74:77]
	v_mfma_f32_16x16x32_bf16 v[118:121], v[162:165], v[178:181], v[118:121]
	v_mfma_f32_16x16x32_bf16 v[114:117], v[170:173], v[178:181], v[114:117]
	v_mfma_f32_16x16x32_bf16 v[102:105], v[162:165], v[186:189], v[102:105]
	v_mfma_f32_16x16x32_bf16 v[98:101], v[170:173], v[186:189], v[98:101]
	v_mfma_f32_16x16x32_bf16 v[86:89], v[162:165], v[194:197], v[86:89]
	v_mfma_f32_16x16x32_bf16 v[82:85], v[170:173], v[194:197], v[82:85]
	v_mfma_f32_16x16x32_bf16 v[70:73], v[162:165], v[202:205], v[70:73]
	v_mfma_f32_16x16x32_bf16 v[66:69], v[170:173], v[202:205], v[66:69]
	v_mfma_f32_16x16x32_bf16 v[118:121], v[166:169], v[182:185], v[118:121]
	v_mfma_f32_16x16x32_bf16 v[114:117], v[174:177], v[182:185], v[114:117]
	v_mfma_f32_16x16x32_bf16 v[102:105], v[166:169], v[190:193], v[102:105]
	v_mfma_f32_16x16x32_bf16 v[98:101], v[174:177], v[190:193], v[98:101]
	v_mfma_f32_16x16x32_bf16 v[86:89], v[166:169], v[198:201], v[86:89]
	v_mfma_f32_16x16x32_bf16 v[82:85], v[174:177], v[198:201], v[82:85]
	v_mfma_f32_16x16x32_bf16 v[70:73], v[166:169], v[206:209], v[70:73]
	v_mfma_f32_16x16x32_bf16 v[66:69], v[174:177], v[206:209], v[66:69]
	s_barrier
	s_nop 0
	s_add_i32 s8, s10, s34
	v_lshl_add_u64 v[210:211], s[28:29], 0, v[130:131]
	s_mov_b32 m0, s8
	ds_read_b128 v[178:181], v145 offset:16384
	ds_read_b128 v[182:185], v145 offset:17408
	ds_read_b128 v[186:189], v145 offset:18432
	ds_read_b128 v[190:193], v145 offset:19456
	ds_read_b128 v[194:197], v145 offset:20480
	ds_read_b128 v[198:201], v145 offset:21504
	ds_read_b128 v[202:205], v145 offset:22528
	ds_read_b128 v[206:209], v145 offset:23552
	global_load_lds_dwordx4 v[210:211], off
	s_add_i32 m0, s8, 0x2000
	s_add_u32 s8, s28, 0x40000
	v_lshl_add_u64 v[212:213], s[28:29], 0, v[132:133]
	s_addc_u32 s9, s29, 0
	s_add_i32 s10, s11, s34
	global_load_lds_dwordx4 v[212:213], off
	v_lshl_add_u64 v[214:215], s[8:9], 0, v[130:131]
	s_mov_b32 m0, s10
	v_lshl_add_u64 v[216:217], s[40:41], 0, v[134:135]
	global_load_lds_dwordx4 v[214:215], off
	v_lshl_add_u64 v[214:215], s[8:9], 0, v[132:133]
	s_add_i32 m0, s10, 0x2000
	s_nop 0
	global_load_lds_dwordx4 v[214:215], off
	v_lshl_add_u64 v[214:215], s[40:41], 0, v[136:137]
	s_mov_b32 m0, s62
	s_nop 0
	global_load_lds_dwordx4 v[214:215], off
	s_mov_b32 m0, s63
	s_nop 0
	global_load_lds_dwordx4 v[216:217], off
	s_waitcnt vmcnt(8)
	s_waitcnt lgkmcnt(0)
	s_nop 0
	s_barrier
	v_mfma_f32_16x16x32_bf16 v[62:65], v[146:149], v[178:181], v[62:65]
	v_mfma_f32_16x16x32_bf16 v[58:61], v[154:157], v[178:181], v[58:61]
	v_mfma_f32_16x16x32_bf16 v[46:49], v[146:149], v[186:189], v[46:49]
	v_mfma_f32_16x16x32_bf16 v[42:45], v[154:157], v[186:189], v[42:45]
	v_mfma_f32_16x16x32_bf16 v[30:33], v[146:149], v[194:197], v[30:33]
	v_mfma_f32_16x16x32_bf16 v[26:29], v[154:157], v[194:197], v[26:29]
	v_mfma_f32_16x16x32_bf16 v[14:17], v[146:149], v[202:205], v[14:17]
	v_mfma_f32_16x16x32_bf16 v[10:13], v[154:157], v[202:205], v[10:13]
	v_mfma_f32_16x16x32_bf16 v[62:65], v[150:153], v[182:185], v[62:65]
	v_mfma_f32_16x16x32_bf16 v[58:61], v[158:161], v[182:185], v[58:61]
	v_mfma_f32_16x16x32_bf16 v[46:49], v[150:153], v[190:193], v[46:49]
	v_mfma_f32_16x16x32_bf16 v[42:45], v[158:161], v[190:193], v[42:45]
	v_mfma_f32_16x16x32_bf16 v[30:33], v[150:153], v[198:201], v[30:33]
	v_mfma_f32_16x16x32_bf16 v[26:29], v[158:161], v[198:201], v[26:29]
	v_mfma_f32_16x16x32_bf16 v[14:17], v[150:153], v[206:209], v[14:17]
	v_mfma_f32_16x16x32_bf16 v[10:13], v[158:161], v[206:209], v[10:13]
	v_mfma_f32_16x16x32_bf16 v[54:57], v[162:165], v[178:181], v[54:57]
	v_mfma_f32_16x16x32_bf16 v[50:53], v[170:173], v[178:181], v[50:53]
	v_mfma_f32_16x16x32_bf16 v[38:41], v[162:165], v[186:189], v[38:41]
	v_mfma_f32_16x16x32_bf16 v[34:37], v[170:173], v[186:189], v[34:37]
	v_mfma_f32_16x16x32_bf16 v[22:25], v[162:165], v[194:197], v[22:25]
	v_mfma_f32_16x16x32_bf16 v[18:21], v[170:173], v[194:197], v[18:21]
	v_mfma_f32_16x16x32_bf16 v[6:9], v[162:165], v[202:205], v[6:9]
	v_mfma_f32_16x16x32_bf16 v[2:5], v[170:173], v[202:205], v[2:5]
	v_mfma_f32_16x16x32_bf16 v[54:57], v[166:169], v[182:185], v[54:57]
	v_mfma_f32_16x16x32_bf16 v[50:53], v[174:177], v[182:185], v[50:53]
	v_mfma_f32_16x16x32_bf16 v[38:41], v[166:169], v[190:193], v[38:41]
	v_mfma_f32_16x16x32_bf16 v[34:37], v[174:177], v[190:193], v[34:37]
	v_mfma_f32_16x16x32_bf16 v[22:25], v[166:169], v[198:201], v[22:25]
	v_mfma_f32_16x16x32_bf16 v[18:21], v[174:177], v[198:201], v[18:21]
	v_mfma_f32_16x16x32_bf16 v[6:9], v[166:169], v[206:209], v[6:9]
	v_mfma_f32_16x16x32_bf16 v[2:5], v[174:177], v[206:209], v[2:5]
	s_barrier
	s_nop 0
	s_add_i32 s10, 0, 0x18000
	s_add_i32 s11, 0, 0x1c000
	v_add_u32_e32 v158, s10, v1
	v_add_u32_e32 v174, s11, v1
	ds_read_b128 v[146:149], v158
	ds_read_b128 v[150:153], v158 offset:1024
	ds_read_b128 v[154:157], v158 offset:2048
	ds_read_b128 v[158:161], v158 offset:3072
	ds_read_b128 v[162:165], v174
	ds_read_b128 v[166:169], v174 offset:1024
	ds_read_b128 v[170:173], v174 offset:2048
	ds_read_b128 v[174:177], v174 offset:3072
	s_add_u32 s8, s40, 0x40000
	s_addc_u32 s9, s41, 0
	s_mov_b32 m0, s64
	v_lshl_add_u64 v[218:219], s[8:9], 0, v[136:137]
	ds_read_b128 v[178:181], v145 offset:32768
	ds_read_b128 v[182:185], v145 offset:33792
	ds_read_b128 v[186:189], v145 offset:34816
	ds_read_b128 v[190:193], v145 offset:35840
	ds_read_b128 v[194:197], v145 offset:36864
	ds_read_b128 v[198:201], v145 offset:37888
	ds_read_b128 v[202:205], v145 offset:38912
	ds_read_b128 v[206:209], v145 offset:39936
	global_load_lds_dwordx4 v[218:219], off
	v_lshl_add_u64 v[218:219], s[8:9], 0, v[134:135]
	s_mov_b32 m0, s65
	s_nop 0
	global_load_lds_dwordx4 v[218:219], off
	s_waitcnt vmcnt(8)
	s_waitcnt lgkmcnt(0)
	s_nop 0
	s_barrier
	v_mfma_f32_16x16x32_bf16 v[126:129], v[146:149], v[178:181], v[126:129]
	v_mfma_f32_16x16x32_bf16 v[122:125], v[154:157], v[178:181], v[122:125]
	v_mfma_f32_16x16x32_bf16 v[110:113], v[146:149], v[186:189], v[110:113]
	v_mfma_f32_16x16x32_bf16 v[106:109], v[154:157], v[186:189], v[106:109]
	v_mfma_f32_16x16x32_bf16 v[94:97], v[146:149], v[194:197], v[94:97]
	v_mfma_f32_16x16x32_bf16 v[90:93], v[154:157], v[194:197], v[90:93]
	v_mfma_f32_16x16x32_bf16 v[78:81], v[146:149], v[202:205], v[78:81]
	v_mfma_f32_16x16x32_bf16 v[74:77], v[154:157], v[202:205], v[74:77]
	v_mfma_f32_16x16x32_bf16 v[126:129], v[150:153], v[182:185], v[126:129]
	v_mfma_f32_16x16x32_bf16 v[122:125], v[158:161], v[182:185], v[122:125]
	v_mfma_f32_16x16x32_bf16 v[110:113], v[150:153], v[190:193], v[110:113]
	v_mfma_f32_16x16x32_bf16 v[106:109], v[158:161], v[190:193], v[106:109]
	v_mfma_f32_16x16x32_bf16 v[94:97], v[150:153], v[198:201], v[94:97]
	v_mfma_f32_16x16x32_bf16 v[90:93], v[158:161], v[198:201], v[90:93]
	v_mfma_f32_16x16x32_bf16 v[78:81], v[150:153], v[206:209], v[78:81]
	v_mfma_f32_16x16x32_bf16 v[74:77], v[158:161], v[206:209], v[74:77]
	v_mfma_f32_16x16x32_bf16 v[118:121], v[162:165], v[178:181], v[118:121]
	v_mfma_f32_16x16x32_bf16 v[114:117], v[170:173], v[178:181], v[114:117]
	v_mfma_f32_16x16x32_bf16 v[102:105], v[162:165], v[186:189], v[102:105]
	v_mfma_f32_16x16x32_bf16 v[98:101], v[170:173], v[186:189], v[98:101]
	v_mfma_f32_16x16x32_bf16 v[86:89], v[162:165], v[194:197], v[86:89]
	v_mfma_f32_16x16x32_bf16 v[82:85], v[170:173], v[194:197], v[82:85]
	v_mfma_f32_16x16x32_bf16 v[70:73], v[162:165], v[202:205], v[70:73]
	v_mfma_f32_16x16x32_bf16 v[66:69], v[170:173], v[202:205], v[66:69]
	v_mfma_f32_16x16x32_bf16 v[118:121], v[166:169], v[182:185], v[118:121]
	v_mfma_f32_16x16x32_bf16 v[114:117], v[174:177], v[182:185], v[114:117]
	v_mfma_f32_16x16x32_bf16 v[102:105], v[166:169], v[190:193], v[102:105]
	v_mfma_f32_16x16x32_bf16 v[98:101], v[174:177], v[190:193], v[98:101]
	v_mfma_f32_16x16x32_bf16 v[86:89], v[166:169], v[198:201], v[86:89]
	v_mfma_f32_16x16x32_bf16 v[82:85], v[174:177], v[198:201], v[82:85]
	v_mfma_f32_16x16x32_bf16 v[70:73], v[166:169], v[206:209], v[70:73]
	v_mfma_f32_16x16x32_bf16 v[66:69], v[174:177], v[206:209], v[66:69]
	s_barrier
	s_nop 0
	s_add_i32 s8, s10, s34
	v_lshl_add_u64 v[210:211], v[210:211], 0, s[82:83]
	s_mov_b32 m0, s8
	ds_read_b128 v[178:181], v145 offset:49152
	ds_read_b128 v[182:185], v145 offset:50176
	ds_read_b128 v[186:189], v145 offset:51200
	ds_read_b128 v[190:193], v145 offset:52224
	ds_read_b128 v[194:197], v145 offset:53248
	ds_read_b128 v[198:201], v145 offset:54272
	ds_read_b128 v[202:205], v145 offset:55296
	ds_read_b128 v[206:209], v145 offset:56320
	global_load_lds_dwordx4 v[210:211], off
	s_add_i32 m0, s8, 0x2000
	s_add_u32 s8, s28, 0x40080
	v_lshl_add_u64 v[210:211], v[212:213], 0, s[82:83]
	s_addc_u32 s9, s29, 0
	s_add_i32 s10, s11, s34
	global_load_lds_dwordx4 v[210:211], off
	v_lshl_add_u64 v[210:211], s[8:9], 0, v[130:131]
	s_mov_b32 m0, s10
	s_nop 0
	global_load_lds_dwordx4 v[210:211], off
	v_lshl_add_u64 v[210:211], s[8:9], 0, v[132:133]
	s_add_i32 m0, s10, 0x2000
	s_nop 0
	global_load_lds_dwordx4 v[210:211], off
	v_lshl_add_u64 v[210:211], v[214:215], 0, s[82:83]
	s_mov_b32 m0, s66
	s_nop 0
	global_load_lds_dwordx4 v[210:211], off
	v_lshl_add_u64 v[210:211], v[216:217], 0, s[82:83]
	s_mov_b32 m0, s67
	s_nop 0
	global_load_lds_dwordx4 v[210:211], off
	s_waitcnt vmcnt(8)
	s_waitcnt lgkmcnt(0)
	s_nop 0
	s_barrier
	v_mfma_f32_16x16x32_bf16 v[62:65], v[146:149], v[178:181], v[62:65]
	v_mfma_f32_16x16x32_bf16 v[58:61], v[154:157], v[178:181], v[58:61]
	v_mfma_f32_16x16x32_bf16 v[46:49], v[146:149], v[186:189], v[46:49]
	v_mfma_f32_16x16x32_bf16 v[42:45], v[154:157], v[186:189], v[42:45]
	v_mfma_f32_16x16x32_bf16 v[30:33], v[146:149], v[194:197], v[30:33]
	v_mfma_f32_16x16x32_bf16 v[26:29], v[154:157], v[194:197], v[26:29]
	v_mfma_f32_16x16x32_bf16 v[14:17], v[146:149], v[202:205], v[14:17]
	v_mfma_f32_16x16x32_bf16 v[10:13], v[154:157], v[202:205], v[10:13]
	v_mfma_f32_16x16x32_bf16 v[62:65], v[150:153], v[182:185], v[62:65]
	v_mfma_f32_16x16x32_bf16 v[58:61], v[158:161], v[182:185], v[58:61]
	v_mfma_f32_16x16x32_bf16 v[46:49], v[150:153], v[190:193], v[46:49]
	v_mfma_f32_16x16x32_bf16 v[42:45], v[158:161], v[190:193], v[42:45]
	v_mfma_f32_16x16x32_bf16 v[30:33], v[150:153], v[198:201], v[30:33]
	v_mfma_f32_16x16x32_bf16 v[26:29], v[158:161], v[198:201], v[26:29]
	v_mfma_f32_16x16x32_bf16 v[14:17], v[150:153], v[206:209], v[14:17]
	v_mfma_f32_16x16x32_bf16 v[10:13], v[158:161], v[206:209], v[10:13]
	v_mfma_f32_16x16x32_bf16 v[54:57], v[162:165], v[178:181], v[54:57]
	v_mfma_f32_16x16x32_bf16 v[50:53], v[170:173], v[178:181], v[50:53]
	v_mfma_f32_16x16x32_bf16 v[38:41], v[162:165], v[186:189], v[38:41]
	v_mfma_f32_16x16x32_bf16 v[34:37], v[170:173], v[186:189], v[34:37]
	v_mfma_f32_16x16x32_bf16 v[22:25], v[162:165], v[194:197], v[22:25]
	v_mfma_f32_16x16x32_bf16 v[18:21], v[170:173], v[194:197], v[18:21]
	v_mfma_f32_16x16x32_bf16 v[6:9], v[162:165], v[202:205], v[6:9]
	v_mfma_f32_16x16x32_bf16 v[2:5], v[170:173], v[202:205], v[2:5]
	v_mfma_f32_16x16x32_bf16 v[54:57], v[166:169], v[182:185], v[54:57]
	v_mfma_f32_16x16x32_bf16 v[50:53], v[174:177], v[182:185], v[50:53]
	v_mfma_f32_16x16x32_bf16 v[38:41], v[166:169], v[190:193], v[38:41]
	v_mfma_f32_16x16x32_bf16 v[34:37], v[174:177], v[190:193], v[34:37]
	v_mfma_f32_16x16x32_bf16 v[22:25], v[166:169], v[198:201], v[22:25]
	v_mfma_f32_16x16x32_bf16 v[18:21], v[174:177], v[198:201], v[18:21]
	v_mfma_f32_16x16x32_bf16 v[6:9], v[166:169], v[206:209], v[6:9]
	v_mfma_f32_16x16x32_bf16 v[2:5], v[174:177], v[206:209], v[2:5]
	s_barrier
	s_nop 0
	s_add_i32 s84, s84, 2
	s_add_u32 s60, s60, 0x100
	s_addc_u32 s61, s61, 0
	s_add_u32 s76, s76, 0x100
	s_addc_u32 s77, s77, 0
	s_cmp_gt_u32 s84, 13
	s_cbranch_scc0 .LBB0_497
	s_and_b64 vcc, exec, s[50:51]
	s_cbranch_vccz .LBB0_500
	s_barrier
